# v45 without the K-loop barrier shift (original barrier placement), to price that edit
# speedup vs baseline: 1.0061x; 1.0061x over previous
; #define PG8_STAGE(bufoff, gbase, voff) do { _Pragma("unroll") for (int _i = 0; _i < 2; ++_i) \
;         __builtin_amdgcn_global_load_lds((const unsigned*)((const char*)(gbase) + (voff)[_i]), (PG8_LAS unsigned*)(lds + (bufoff) + ldsw + _i * 8192), 16, 0, 0); } while (0)
; #define PG8_LDA(dst, b, h) do { _Pragma("unroll") for (int m = 0; m < 4; ++m) _Pragma("unroll") for (int k = 0; k < 2; ++k) dst[m][k] = *(const PG8_LAS bf16x8*)(lds + PG8_SA(b, h) + aoff + m * 2048 + k * 1024); } while (0)
; #define PG8_LDB(dst, b, h) do { _Pragma("unroll") for (int n = 0; n < 2; ++n) _Pragma("unroll") for (int k = 0; k < 2; ++k) dst[n][k] = *(const PG8_LAS bf16x8*)(lds + PG8_SB(b, h) + boff + n * 2048 + k * 1024); } while (0)
; #define PG8_MMA(ai, bj, At, Bt) do { __builtin_amdgcn_s_setprio(1); _Pragma("unroll") for (int m = 0; m < 4; ++m) _Pragma("unroll") for (int n = 0; n < 2; ++n) _Pragma("unroll") for (int k = 0; k < 2; ++k) \
;         acc[ai][bj][m][n] = __builtin_amdgcn_mfma_f32_16x16x32_bf16(Bt[n][k], At[m][k], acc[ai][bj][m][n], 0, 0, 0); __builtin_amdgcn_s_setprio(0); } while (0)
; #define PG8_WAIT_V(n) asm volatile("s_waitcnt vmcnt(" #n ")" ::: "memory")
; #define PG8_WAIT_L(n) asm volatile("s_waitcnt lgkmcnt(" #n ")" ::: "memory")
; template <class Epi, class Sched, bool ALIGN_EPI = false, bool SP2 = false>
; __device__ __forceinline__ void gemm_phase(PG8_LAS unsigned char* lds, const Gemm g, const Sched& S, const Epi& E, int wave_in) {
;     ...
;             const bool last = (t == nt - 2);
;             const char* a1 = cA + (size_t)(t + 1) * kstep;
;             const char* a2 = last ? nA : cA + (size_t)(t + 2) * kstep; const char* b2 = last ? nB : cB + (size_t)(t + 2) * kstep;
;             const char* a3 = a2 + kstep; const char* b3 = b2 + kstep;
;             if (last && has_next) S.a_ready(nxt);
;             if constexpr (SP2) {
;             PG8_LDB(B0, 0, 0); PG8_LDB(B1, 0, 1); PG8_SCHED; PG8_LDA(At, 0, 0); PG8_STAGE(PG8_SA(1, 1), a1 + hstep, voffA);
;             PG8_WAIT_V(8); PG8_WAIT_L(0); PG8_BAR; PG8_MMA(0, 0, At, B0); PG8_MMA(0, 1, At, B1); PG8_BAR; PG8_SCHED;
;             PG8_LDA(At, 0, 1); PG8_STAGE(PG8_SB(0, 0), b2, voffB); PG8_STAGE(PG8_SB(0, 1), b2 + hstep, voffB); PG8_STAGE(PG8_SA(0, 0), a2, voffA);
;             PG8_WAIT_V(8); PG8_WAIT_L(0); PG8_BAR; PG8_MMA(1, 0, At, B0); PG8_MMA(1, 1, At, B1); PG8_BAR; PG8_SCHED;
.LBB0_845:
	ds_read_b128 v[140:143], v147
	ds_read_b128 v[152:155], v147 offset:1024
	ds_read_b128 v[156:159], v147 offset:2048
	ds_read_b128 v[160:163], v147 offset:3072
	ds_read_b128 v[164:167], v148
	ds_read_b128 v[168:171], v148 offset:1024
	ds_read_b128 v[172:175], v148 offset:2048
	ds_read_b128 v[176:179], v148 offset:3072
	s_add_u32 s26, s24, 0xfff80080
	s_addc_u32 s27, s25, -1
	s_cmp_eq_u32 s48, 28
	s_cselect_b32 s29, s15, s27
	s_cselect_b32 s28, s21, s26
	s_cselect_b32 s27, s13, s47
	s_cselect_b32 s26, s45, s46
	v_lshl_add_u64 v[212:213], s[24:25], 0, v[132:133]
	s_add_i32 m0, s23, 0xc000
	ds_read_b128 v[180:183], v149
	ds_read_b128 v[184:187], v149 offset:1024
	ds_read_b128 v[188:191], v149 offset:2048
	ds_read_b128 v[192:195], v149 offset:3072
	ds_read_b128 v[196:199], v149 offset:4096
	ds_read_b128 v[200:203], v149 offset:5120
	ds_read_b128 v[204:207], v149 offset:6144
	ds_read_b128 v[208:211], v149 offset:7168
	global_load_lds_dwordx4 v[212:213], off
	v_lshl_add_u64 v[212:213], s[24:25], 0, v[134:135]
	s_add_i32 m0, s23, 0xe000
	s_nop 0
	global_load_lds_dwordx4 v[212:213], off
	s_waitcnt vmcnt(8)
	s_waitcnt lgkmcnt(0)
	s_barrier
	s_setprio 1
	s_waitcnt lgkmcnt(0)
	v_mfma_f32_16x16x32_bf16 v[124:127], v[140:143], v[180:183], v[124:127]
	v_mfma_f32_16x16x32_bf16 v[120:123], v[156:159], v[180:183], v[120:123]
	v_mfma_f32_16x16x32_bf16 v[108:111], v[140:143], v[188:191], v[108:111]
	v_mfma_f32_16x16x32_bf16 v[104:107], v[156:159], v[188:191], v[104:107]
	v_mfma_f32_16x16x32_bf16 v[92:95], v[140:143], v[196:199], v[92:95]
	v_mfma_f32_16x16x32_bf16 v[88:91], v[156:159], v[196:199], v[88:91]
	v_mfma_f32_16x16x32_bf16 v[76:79], v[140:143], v[204:207], v[76:79]
	v_mfma_f32_16x16x32_bf16 v[72:75], v[156:159], v[204:207], v[72:75]
	v_mfma_f32_16x16x32_bf16 v[124:127], v[152:155], v[184:187], v[124:127]
	v_mfma_f32_16x16x32_bf16 v[120:123], v[160:163], v[184:187], v[120:123]
	v_mfma_f32_16x16x32_bf16 v[108:111], v[152:155], v[192:195], v[108:111]
	v_mfma_f32_16x16x32_bf16 v[104:107], v[160:163], v[192:195], v[104:107]
	v_mfma_f32_16x16x32_bf16 v[92:95], v[152:155], v[200:203], v[92:95]
	v_mfma_f32_16x16x32_bf16 v[88:91], v[160:163], v[200:203], v[88:91]
	v_mfma_f32_16x16x32_bf16 v[76:79], v[152:155], v[208:211], v[76:79]
	v_mfma_f32_16x16x32_bf16 v[72:75], v[160:163], v[208:211], v[72:75]
	s_setprio 0
	s_setprio 1
	v_mfma_f32_16x16x32_bf16 v[116:119], v[164:167], v[180:183], v[116:119]
	v_mfma_f32_16x16x32_bf16 v[112:115], v[172:175], v[180:183], v[112:115]
	v_mfma_f32_16x16x32_bf16 v[100:103], v[164:167], v[188:191], v[100:103]
	v_mfma_f32_16x16x32_bf16 v[96:99], v[172:175], v[188:191], v[96:99]
	v_mfma_f32_16x16x32_bf16 v[84:87], v[164:167], v[196:199], v[84:87]
	v_mfma_f32_16x16x32_bf16 v[80:83], v[172:175], v[196:199], v[80:83]
	v_mfma_f32_16x16x32_bf16 v[68:71], v[164:167], v[204:207], v[68:71]
	v_mfma_f32_16x16x32_bf16 v[64:67], v[172:175], v[204:207], v[64:67]
	v_mfma_f32_16x16x32_bf16 v[116:119], v[168:171], v[184:187], v[116:119]
	v_mfma_f32_16x16x32_bf16 v[112:115], v[176:179], v[184:187], v[112:115]
	v_mfma_f32_16x16x32_bf16 v[100:103], v[168:171], v[192:195], v[100:103]
	v_mfma_f32_16x16x32_bf16 v[96:99], v[176:179], v[192:195], v[96:99]
	v_mfma_f32_16x16x32_bf16 v[84:87], v[168:171], v[200:203], v[84:87]
	v_mfma_f32_16x16x32_bf16 v[80:83], v[176:179], v[200:203], v[80:83]
	v_mfma_f32_16x16x32_bf16 v[68:71], v[168:171], v[208:211], v[68:71]
	v_mfma_f32_16x16x32_bf16 v[64:67], v[176:179], v[208:211], v[64:67]
	s_setprio 0
	s_barrier
	s_add_i32 s49, s43, s30
	v_lshl_add_u64 v[212:213], s[26:27], 0, v[128:129]
	s_mov_b32 m0, s49
	ds_read_b128 v[180:183], v149 offset:16384
	ds_read_b128 v[184:187], v149 offset:17408
	ds_read_b128 v[188:191], v149 offset:18432
	ds_read_b128 v[192:195], v149 offset:19456
	ds_read_b128 v[196:199], v149 offset:20480
	ds_read_b128 v[200:203], v149 offset:21504
	ds_read_b128 v[204:207], v149 offset:22528
	ds_read_b128 v[208:211], v149 offset:23552
	global_load_lds_dwordx4 v[212:213], off
	s_add_i32 m0, s49, 0x2000
	s_add_u32 s50, s26, 0x80000
	v_lshl_add_u64 v[214:215], s[26:27], 0, v[130:131]
	s_addc_u32 s51, s27, 0
	s_add_i32 s49, s44, s30
	global_load_lds_dwordx4 v[214:215], off
	v_lshl_add_u64 v[216:217], s[50:51], 0, v[128:129]
	s_mov_b32 m0, s49
	v_lshl_add_u64 v[218:219], s[28:29], 0, v[130:131]
	global_load_lds_dwordx4 v[216:217], off
	v_lshl_add_u64 v[216:217], s[50:51], 0, v[130:131]
	s_add_i32 m0, s49, 0x2000
	s_nop 0
	global_load_lds_dwordx4 v[216:217], off
	v_lshl_add_u64 v[216:217], s[28:29], 0, v[128:129]
	s_mov_b32 m0, s23
	s_nop 0
	global_load_lds_dwordx4 v[216:217], off
	s_mov_b32 m0, s34
	s_nop 0
	global_load_lds_dwordx4 v[218:219], off
	s_waitcnt vmcnt(8)
	s_waitcnt lgkmcnt(0)
	s_barrier
; #define PG8_STAGE(bufoff, gbase, voff) do { _Pragma("unroll") for (int _i = 0; _i < 2; ++_i) \
;         __builtin_amdgcn_global_load_lds((const unsigned*)((const char*)(gbase) + (voff)[_i]), (PG8_LAS unsigned*)(lds + (bufoff) + ldsw + _i * 8192), 16, 0, 0); } while (0)
; #define PG8_LDA(dst, b, h) do { _Pragma("unroll") for (int m = 0; m < 4; ++m) _Pragma("unroll") for (int k = 0; k < 2; ++k) dst[m][k] = *(const PG8_LAS bf16x8*)(lds + PG8_SA(b, h) + aoff + m * 2048 + k * 1024); } while (0)
; #define PG8_LDB(dst, b, h) do { _Pragma("unroll") for (int n = 0; n < 2; ++n) _Pragma("unroll") for (int k = 0; k < 2; ++k) dst[n][k] = *(const PG8_LAS bf16x8*)(lds + PG8_SB(b, h) + boff + n * 2048 + k * 1024); } while (0)
; #define PG8_MMA(ai, bj, At, Bt) do { __builtin_amdgcn_s_setprio(1); _Pragma("unroll") for (int m = 0; m < 4; ++m) _Pragma("unroll") for (int n = 0; n < 2; ++n) _Pragma("unroll") for (int k = 0; k < 2; ++k) \
;         acc[ai][bj][m][n] = __builtin_amdgcn_mfma_f32_16x16x32_bf16(Bt[n][k], At[m][k], acc[ai][bj][m][n], 0, 0, 0); __builtin_amdgcn_s_setprio(0); } while (0)
; #define PG8_WAIT_V(n) asm volatile("s_waitcnt vmcnt(" #n ")" ::: "memory")
; #define PG8_WAIT_L(n) asm volatile("s_waitcnt lgkmcnt(" #n ")" ::: "memory")
; #define PG8_BAR __builtin_amdgcn_s_barrier()
; #define PG8_SCHED __builtin_amdgcn_sched_barrier(0)
; template <class Epi, class Sched, bool ALIGN_EPI = false, bool SP2 = false>
; __device__ __forceinline__ void gemm_phase(PG8_LAS unsigned char* lds, const Gemm g, const Sched& S, const Epi& E, int wave_in) {
;     ...
;             PG8_LDA(At, 0, 1); PG8_STAGE(PG8_SB(0, 0), b2, voffB); PG8_STAGE(PG8_SB(0, 1), b2 + hstep, voffB); PG8_STAGE(PG8_SA(0, 0), a2, voffA);
;             PG8_WAIT_V(8); PG8_WAIT_L(0); PG8_BAR; PG8_MMA(1, 0, At, B0); PG8_MMA(1, 1, At, B1); PG8_BAR; PG8_SCHED;
;             PG8_LDB(B0, 1, 0); PG8_LDB(B1, 1, 1); PG8_SCHED; PG8_LDA(At, 1, 0); PG8_STAGE(PG8_SA(0, 1), a2 + hstep, voffA);
;             PG8_WAIT_V(8); PG8_WAIT_L(0); PG8_BAR; PG8_MMA(0, 0, At, B0); PG8_MMA(0, 1, At, B1); PG8_BAR; PG8_SCHED;
	s_setprio 1
	s_waitcnt lgkmcnt(0)
	v_mfma_f32_16x16x32_bf16 v[60:63], v[140:143], v[180:183], v[60:63]
	v_mfma_f32_16x16x32_bf16 v[56:59], v[156:159], v[180:183], v[56:59]
	v_mfma_f32_16x16x32_bf16 v[44:47], v[140:143], v[188:191], v[44:47]
	v_mfma_f32_16x16x32_bf16 v[40:43], v[156:159], v[188:191], v[40:43]
	v_mfma_f32_16x16x32_bf16 v[28:31], v[140:143], v[196:199], v[28:31]
	v_mfma_f32_16x16x32_bf16 v[24:27], v[156:159], v[196:199], v[24:27]
	v_mfma_f32_16x16x32_bf16 v[12:15], v[140:143], v[204:207], v[12:15]
	v_mfma_f32_16x16x32_bf16 v[8:11], v[156:159], v[204:207], v[8:11]
	v_mfma_f32_16x16x32_bf16 v[60:63], v[152:155], v[184:187], v[60:63]
	v_mfma_f32_16x16x32_bf16 v[56:59], v[160:163], v[184:187], v[56:59]
	v_mfma_f32_16x16x32_bf16 v[44:47], v[152:155], v[192:195], v[44:47]
	v_mfma_f32_16x16x32_bf16 v[40:43], v[160:163], v[192:195], v[40:43]
	v_mfma_f32_16x16x32_bf16 v[28:31], v[152:155], v[200:203], v[28:31]
	v_mfma_f32_16x16x32_bf16 v[24:27], v[160:163], v[200:203], v[24:27]
	v_mfma_f32_16x16x32_bf16 v[12:15], v[152:155], v[208:211], v[12:15]
	v_mfma_f32_16x16x32_bf16 v[8:11], v[160:163], v[208:211], v[8:11]
	s_setprio 0
	s_setprio 1
	v_mfma_f32_16x16x32_bf16 v[52:55], v[164:167], v[180:183], v[52:55]
	v_mfma_f32_16x16x32_bf16 v[48:51], v[172:175], v[180:183], v[48:51]
	v_mfma_f32_16x16x32_bf16 v[36:39], v[164:167], v[188:191], v[36:39]
	v_mfma_f32_16x16x32_bf16 v[32:35], v[172:175], v[188:191], v[32:35]
	v_mfma_f32_16x16x32_bf16 v[20:23], v[164:167], v[196:199], v[20:23]
	v_mfma_f32_16x16x32_bf16 v[16:19], v[172:175], v[196:199], v[16:19]
	v_mfma_f32_16x16x32_bf16 v[4:7], v[164:167], v[204:207], v[4:7]
	v_mfma_f32_16x16x32_bf16 v[0:3], v[172:175], v[204:207], v[0:3]
	v_mfma_f32_16x16x32_bf16 v[52:55], v[168:171], v[184:187], v[52:55]
	v_mfma_f32_16x16x32_bf16 v[48:51], v[176:179], v[184:187], v[48:51]
	v_mfma_f32_16x16x32_bf16 v[36:39], v[168:171], v[192:195], v[36:39]
	v_mfma_f32_16x16x32_bf16 v[32:35], v[176:179], v[192:195], v[32:35]
	v_mfma_f32_16x16x32_bf16 v[20:23], v[168:171], v[200:203], v[20:23]
	v_mfma_f32_16x16x32_bf16 v[16:19], v[176:179], v[200:203], v[16:19]
	v_mfma_f32_16x16x32_bf16 v[4:7], v[168:171], v[208:211], v[4:7]
	v_mfma_f32_16x16x32_bf16 v[0:3], v[176:179], v[208:211], v[0:3]
	s_setprio 0
	s_barrier
	s_add_i32 s49, 0, 0x18000
	v_add_u32_e32 v151, s49, v145
	s_add_i32 s50, 0, 0x1c000
	ds_read_b128 v[140:143], v151
	ds_read_b128 v[152:155], v151 offset:1024
	ds_read_b128 v[156:159], v151 offset:2048
	ds_read_b128 v[160:163], v151 offset:3072
	v_add_u32_e32 v151, s50, v145
	ds_read_b128 v[164:167], v151
	ds_read_b128 v[168:171], v151 offset:1024
	ds_read_b128 v[172:175], v151 offset:2048
	ds_read_b128 v[176:179], v151 offset:3072
	s_add_u32 s28, s28, 0x80000
	s_addc_u32 s29, s29, 0
	s_mov_b32 m0, s35
	v_lshl_add_u64 v[220:221], s[28:29], 0, v[128:129]
	ds_read_b128 v[180:183], v149 offset:32768
	ds_read_b128 v[184:187], v149 offset:33792
	ds_read_b128 v[188:191], v149 offset:34816
	ds_read_b128 v[192:195], v149 offset:35840
	ds_read_b128 v[196:199], v149 offset:36864
	ds_read_b128 v[200:203], v149 offset:37888
	ds_read_b128 v[204:207], v149 offset:38912
	ds_read_b128 v[208:211], v149 offset:39936
	global_load_lds_dwordx4 v[220:221], off
	v_lshl_add_u64 v[220:221], s[28:29], 0, v[130:131]
	s_mov_b32 m0, s36
	s_nop 0
	global_load_lds_dwordx4 v[220:221], off
	s_waitcnt vmcnt(8)
	s_waitcnt lgkmcnt(0)
	s_barrier
	s_setprio 1
	s_waitcnt lgkmcnt(0)
	v_mfma_f32_16x16x32_bf16 v[124:127], v[140:143], v[180:183], v[124:127]
	v_mfma_f32_16x16x32_bf16 v[120:123], v[156:159], v[180:183], v[120:123]
	v_mfma_f32_16x16x32_bf16 v[108:111], v[140:143], v[188:191], v[108:111]
	v_mfma_f32_16x16x32_bf16 v[104:107], v[156:159], v[188:191], v[104:107]
	v_mfma_f32_16x16x32_bf16 v[92:95], v[140:143], v[196:199], v[92:95]
	v_mfma_f32_16x16x32_bf16 v[88:91], v[156:159], v[196:199], v[88:91]
	v_mfma_f32_16x16x32_bf16 v[76:79], v[140:143], v[204:207], v[76:79]
	v_mfma_f32_16x16x32_bf16 v[72:75], v[156:159], v[204:207], v[72:75]
	v_mfma_f32_16x16x32_bf16 v[124:127], v[152:155], v[184:187], v[124:127]
	v_mfma_f32_16x16x32_bf16 v[120:123], v[160:163], v[184:187], v[120:123]
	v_mfma_f32_16x16x32_bf16 v[108:111], v[152:155], v[192:195], v[108:111]
	v_mfma_f32_16x16x32_bf16 v[104:107], v[160:163], v[192:195], v[104:107]
	v_mfma_f32_16x16x32_bf16 v[92:95], v[152:155], v[200:203], v[92:95]
	v_mfma_f32_16x16x32_bf16 v[88:91], v[160:163], v[200:203], v[88:91]
	v_mfma_f32_16x16x32_bf16 v[76:79], v[152:155], v[208:211], v[76:79]
	v_mfma_f32_16x16x32_bf16 v[72:75], v[160:163], v[208:211], v[72:75]
	s_setprio 0
	s_setprio 1
	v_mfma_f32_16x16x32_bf16 v[116:119], v[164:167], v[180:183], v[116:119]
	v_mfma_f32_16x16x32_bf16 v[112:115], v[172:175], v[180:183], v[112:115]
	v_mfma_f32_16x16x32_bf16 v[100:103], v[164:167], v[188:191], v[100:103]
	v_mfma_f32_16x16x32_bf16 v[96:99], v[172:175], v[188:191], v[96:99]
	v_mfma_f32_16x16x32_bf16 v[84:87], v[164:167], v[196:199], v[84:87]
	v_mfma_f32_16x16x32_bf16 v[80:83], v[172:175], v[196:199], v[80:83]
	v_mfma_f32_16x16x32_bf16 v[68:71], v[164:167], v[204:207], v[68:71]
	v_mfma_f32_16x16x32_bf16 v[64:67], v[172:175], v[204:207], v[64:67]
	v_mfma_f32_16x16x32_bf16 v[116:119], v[168:171], v[184:187], v[116:119]
	v_mfma_f32_16x16x32_bf16 v[112:115], v[176:179], v[184:187], v[112:115]
	v_mfma_f32_16x16x32_bf16 v[100:103], v[168:171], v[192:195], v[100:103]
	v_mfma_f32_16x16x32_bf16 v[96:99], v[176:179], v[192:195], v[96:99]
	v_mfma_f32_16x16x32_bf16 v[84:87], v[168:171], v[200:203], v[84:87]
	v_mfma_f32_16x16x32_bf16 v[80:83], v[176:179], v[200:203], v[80:83]
	v_mfma_f32_16x16x32_bf16 v[68:71], v[168:171], v[208:211], v[68:71]
	v_mfma_f32_16x16x32_bf16 v[64:67], v[176:179], v[208:211], v[64:67]
	s_setprio 0
	s_barrier
; #define PG8_STAGE(bufoff, gbase, voff) do { _Pragma("unroll") for (int _i = 0; _i < 2; ++_i) \
;         __builtin_amdgcn_global_load_lds((const unsigned*)((const char*)(gbase) + (voff)[_i]), (PG8_LAS unsigned*)(lds + (bufoff) + ldsw + _i * 8192), 16, 0, 0); } while (0)
; #define PG8_LDA(dst, b, h) do { _Pragma("unroll") for (int m = 0; m < 4; ++m) _Pragma("unroll") for (int k = 0; k < 2; ++k) dst[m][k] = *(const PG8_LAS bf16x8*)(lds + PG8_SA(b, h) + aoff + m * 2048 + k * 1024); } while (0)
; #define PG8_MMA(ai, bj, At, Bt) do { __builtin_amdgcn_s_setprio(1); _Pragma("unroll") for (int m = 0; m < 4; ++m) _Pragma("unroll") for (int n = 0; n < 2; ++n) _Pragma("unroll") for (int k = 0; k < 2; ++k) \
;         acc[ai][bj][m][n] = __builtin_amdgcn_mfma_f32_16x16x32_bf16(Bt[n][k], At[m][k], acc[ai][bj][m][n], 0, 0, 0); __builtin_amdgcn_s_setprio(0); } while (0)
; #define PG8_WAIT_V(n) asm volatile("s_waitcnt vmcnt(" #n ")" ::: "memory")
; #define PG8_WAIT_L(n) asm volatile("s_waitcnt lgkmcnt(" #n ")" ::: "memory")
; #define PG8_BAR __builtin_amdgcn_s_barrier()
; #define PG8_SCHED __builtin_amdgcn_sched_barrier(0)
;     __device__ __forceinline__ void operator()(const f32x4 (&acc)[2][2][4][2], const Unit& u, int wr, int wc, int fr, int fq) const {
;     ...
;             for (int m = 0; m < 4; ++m) { const int row = u.pm * BM + ai * HALF + wr * 64 + m * 16 + fr; const size_t off = (size_t)row * ldc + col0;
;                 float ss = 0.f;
; #pragma unroll
;                 for (int bj = 0; bj < 2; ++bj)
; #pragma unroll
;                     for (int n = 0; n < 2; ++n) { f32x4 bs;
;                         if (BASE_BF16) { const u32x2 t = *(const u32x2*)((const bf16_t*)base + off + bj * HALF + n * 16);
; template <class Epi, class Sched, bool ALIGN_EPI = false, bool SP2 = false>
; __device__ __forceinline__ void gemm_phase(PG8_LAS unsigned char* lds, const Gemm g, const Sched& S, const Epi& E, int wave_in) {
;     ...
;             PG8_WAIT_V(8); PG8_WAIT_L(0); PG8_BAR; PG8_MMA(0, 0, At, B0); PG8_MMA(0, 1, At, B1); PG8_BAR; PG8_SCHED;
;             PG8_LDA(At, 1, 1); PG8_STAGE(PG8_SB(1, 0), b3, voffB); PG8_STAGE(PG8_SB(1, 1), b3 + hstep, voffB); PG8_STAGE(PG8_SA(1, 0), a3, voffA);
;             PG8_WAIT_V(8); PG8_WAIT_L(0); PG8_BAR; PG8_MMA(1, 0, At, B0); PG8_MMA(1, 1, At, B1); PG8_BAR; PG8_SCHED;
	s_add_i32 s28, s49, s30
	v_lshl_add_u64 v[212:213], v[212:213], 0, s[2:3]
	s_mov_b32 m0, s28
	ds_read_b128 v[180:183], v149 offset:49152
	ds_read_b128 v[184:187], v149 offset:50176
	ds_read_b128 v[188:191], v149 offset:51200
	ds_read_b128 v[192:195], v149 offset:52224
	ds_read_b128 v[196:199], v149 offset:53248
	ds_read_b128 v[200:203], v149 offset:54272
	ds_read_b128 v[204:207], v149 offset:55296
	ds_read_b128 v[208:211], v149 offset:56320
	global_load_lds_dwordx4 v[212:213], off
	s_add_i32 m0, s28, 0x2000
	s_add_u32 s26, s26, 0x80080
	v_lshl_add_u64 v[212:213], v[214:215], 0, s[2:3]
	s_addc_u32 s27, s27, 0
	s_add_i32 s28, s50, s30
	global_load_lds_dwordx4 v[212:213], off
	v_lshl_add_u64 v[212:213], s[26:27], 0, v[128:129]
	s_mov_b32 m0, s28
	s_nop 0
	global_load_lds_dwordx4 v[212:213], off
	v_lshl_add_u64 v[212:213], s[26:27], 0, v[130:131]
	s_add_i32 m0, s28, 0x2000
	s_nop 0
	global_load_lds_dwordx4 v[212:213], off
	v_lshl_add_u64 v[212:213], v[216:217], 0, s[2:3]
	s_mov_b32 m0, s38
	s_nop 0
	global_load_lds_dwordx4 v[212:213], off
	v_lshl_add_u64 v[212:213], v[218:219], 0, s[2:3]
	s_mov_b32 m0, s39
	s_nop 0
	global_load_lds_dwordx4 v[212:213], off
	s_waitcnt vmcnt(8)
	s_waitcnt lgkmcnt(0)
	s_barrier
	s_setprio 1
	s_waitcnt lgkmcnt(0)
	v_mfma_f32_16x16x32_bf16 v[60:63], v[140:143], v[180:183], v[60:63]
	v_mfma_f32_16x16x32_bf16 v[56:59], v[156:159], v[180:183], v[56:59]
	v_mfma_f32_16x16x32_bf16 v[44:47], v[140:143], v[188:191], v[44:47]
	v_mfma_f32_16x16x32_bf16 v[40:43], v[156:159], v[188:191], v[40:43]
	v_mfma_f32_16x16x32_bf16 v[28:31], v[140:143], v[196:199], v[28:31]
	v_mfma_f32_16x16x32_bf16 v[24:27], v[156:159], v[196:199], v[24:27]
	v_mfma_f32_16x16x32_bf16 v[12:15], v[140:143], v[204:207], v[12:15]
	v_mfma_f32_16x16x32_bf16 v[8:11], v[156:159], v[204:207], v[8:11]
	v_mfma_f32_16x16x32_bf16 v[60:63], v[152:155], v[184:187], v[60:63]
	v_mfma_f32_16x16x32_bf16 v[56:59], v[160:163], v[184:187], v[56:59]
	v_mfma_f32_16x16x32_bf16 v[44:47], v[152:155], v[192:195], v[44:47]
	v_mfma_f32_16x16x32_bf16 v[40:43], v[160:163], v[192:195], v[40:43]
	v_mfma_f32_16x16x32_bf16 v[28:31], v[152:155], v[200:203], v[28:31]
	v_mfma_f32_16x16x32_bf16 v[24:27], v[160:163], v[200:203], v[24:27]
	v_mfma_f32_16x16x32_bf16 v[12:15], v[152:155], v[208:211], v[12:15]
	v_mfma_f32_16x16x32_bf16 v[8:11], v[160:163], v[208:211], v[8:11]
	s_setprio 0
	s_setprio 1
	v_mfma_f32_16x16x32_bf16 v[52:55], v[164:167], v[180:183], v[52:55]
	v_mfma_f32_16x16x32_bf16 v[48:51], v[172:175], v[180:183], v[48:51]
	v_mfma_f32_16x16x32_bf16 v[36:39], v[164:167], v[188:191], v[36:39]
	v_mfma_f32_16x16x32_bf16 v[32:35], v[172:175], v[188:191], v[32:35]
	v_mfma_f32_16x16x32_bf16 v[20:23], v[164:167], v[196:199], v[20:23]
	v_mfma_f32_16x16x32_bf16 v[16:19], v[172:175], v[196:199], v[16:19]
	v_mfma_f32_16x16x32_bf16 v[4:7], v[164:167], v[204:207], v[4:7]
	v_mfma_f32_16x16x32_bf16 v[0:3], v[172:175], v[204:207], v[0:3]
	v_mfma_f32_16x16x32_bf16 v[52:55], v[168:171], v[184:187], v[52:55]
	v_mfma_f32_16x16x32_bf16 v[48:51], v[176:179], v[184:187], v[48:51]
	v_mfma_f32_16x16x32_bf16 v[36:39], v[168:171], v[192:195], v[36:39]
	v_mfma_f32_16x16x32_bf16 v[32:35], v[176:179], v[192:195], v[32:35]
	v_mfma_f32_16x16x32_bf16 v[20:23], v[168:171], v[200:203], v[20:23]
	v_mfma_f32_16x16x32_bf16 v[16:19], v[176:179], v[200:203], v[16:19]
	v_mfma_f32_16x16x32_bf16 v[4:7], v[168:171], v[208:211], v[4:7]
	v_mfma_f32_16x16x32_bf16 v[0:3], v[176:179], v[208:211], v[0:3]
	s_setprio 0
	s_barrier
	s_add_i32 s48, s48, 2
	s_add_u32 s24, s24, 0x100
	s_addc_u32 s25, s25, 0
	s_add_u32 s46, s46, 0x100
	s_addc_u32 s47, s47, 0
	s_cmp_gt_u32 s48, 29
	s_cbranch_scc0 .LBB0_845
	v_lshl_add_u32 v142, s20, 8, v144
	v_lshl_or_b32 v140, s22, 8, v146
	v_lshlrev_b32_e32 v143, 12, v142
	v_lshl_add_u32 v143, v140, 1, v143
	v_lshlrev_b32_e32 v142, 2, v142
	v_xor_b32_e32 v151, 16, v150
	v_xor_b32_e32 v141, 32, v150
	v_lshlrev_b32_e32 v151, 2, v151
	v_lshlrev_b32_e32 v141, 2, v141
	v_mov_b32_e32 v140, v143
	global_load_dwordx2 v[152:153], v140, s[76:77]
	global_load_dwordx2 v[154:155], v140, s[76:77] offset:32
	global_load_dwordx2 v[156:157], v140, s[76:77] offset:256
	global_load_dwordx2 v[158:159], v140, s[76:77] offset:288
	v_add_u32_e32 v140, 0x10000, v143
	global_load_dwordx2 v[160:161], v140, s[76:77]
	global_load_dwordx2 v[162:163], v140, s[76:77] offset:32
	global_load_dwordx2 v[164:165], v140, s[76:77] offset:256
	global_load_dwordx2 v[166:167], v140, s[76:77] offset:288
	v_add_u32_e32 v140, 0x20000, v143
	global_load_dwordx2 v[168:169], v140, s[76:77]
	global_load_dwordx2 v[170:171], v140, s[76:77] offset:32
	global_load_dwordx2 v[172:173], v140, s[76:77] offset:256
	global_load_dwordx2 v[174:175], v140, s[76:77] offset:288
	v_add_u32_e32 v140, 0x30000, v143
	global_load_dwordx2 v[176:177], v140, s[76:77]
	global_load_dwordx2 v[178:179], v140, s[76:77] offset:32
	global_load_dwordx2 v[180:181], v140, s[76:77] offset:256
	global_load_dwordx2 v[182:183], v140, s[76:77] offset:288
	v_add_u32_e32 v140, 0x80000, v143
	global_load_dwordx2 v[184:185], v140, s[76:77]
	global_load_dwordx2 v[186:187], v140, s[76:77] offset:32
	global_load_dwordx2 v[188:189], v140, s[76:77] offset:256
	global_load_dwordx2 v[190:191], v140, s[76:77] offset:288
	v_add_u32_e32 v140, 0x90000, v143
	global_load_dwordx2 v[192:193], v140, s[76:77]
	global_load_dwordx2 v[194:195], v140, s[76:77] offset:32
	global_load_dwordx2 v[196:197], v140, s[76:77] offset:256
	global_load_dwordx2 v[198:199], v140, s[76:77] offset:288
	v_add_u32_e32 v140, 0xa0000, v143
	global_load_dwordx2 v[200:201], v140, s[76:77]
	global_load_dwordx2 v[202:203], v140, s[76:77] offset:32
	global_load_dwordx2 v[204:205], v140, s[76:77] offset:256
	global_load_dwordx2 v[206:207], v140, s[76:77] offset:288
	s_and_b64 vcc, exec, s[4:5]
	s_cbranch_vccz .LBB0_848
	s_barrier

; #define PG8_STAGE(bufoff, gbase, voff) do { _Pragma("unroll") for (int _i = 0; _i < 2; ++_i) \
;         __builtin_amdgcn_global_load_lds((const unsigned*)((const char*)(gbase) + (voff)[_i]), (PG8_LAS unsigned*)(lds + (bufoff) + ldsw + _i * 8192), 16, 0, 0); } while (0)
; #define PG8_LDA(dst, b, h) do { _Pragma("unroll") for (int m = 0; m < 4; ++m) _Pragma("unroll") for (int k = 0; k < 2; ++k) dst[m][k] = *(const PG8_LAS bf16x8*)(lds + PG8_SA(b, h) + aoff + m * 2048 + k * 1024); } while (0)
; #define PG8_LDB(dst, b, h) do { _Pragma("unroll") for (int n = 0; n < 2; ++n) _Pragma("unroll") for (int k = 0; k < 2; ++k) dst[n][k] = *(const PG8_LAS bf16x8*)(lds + PG8_SB(b, h) + boff + n * 2048 + k * 1024); } while (0)
; #define PG8_MMA(ai, bj, At, Bt) do { __builtin_amdgcn_s_setprio(1); _Pragma("unroll") for (int m = 0; m < 4; ++m) _Pragma("unroll") for (int n = 0; n < 2; ++n) _Pragma("unroll") for (int k = 0; k < 2; ++k) \
;         acc[ai][bj][m][n] = __builtin_amdgcn_mfma_f32_16x16x32_bf16(Bt[n][k], At[m][k], acc[ai][bj][m][n], 0, 0, 0); __builtin_amdgcn_s_setprio(0); } while (0)
; #define PG8_WAIT_V(n) asm volatile("s_waitcnt vmcnt(" #n ")" ::: "memory")
; #define PG8_WAIT_L(n) asm volatile("s_waitcnt lgkmcnt(" #n ")" ::: "memory")
; template <class Epi, class Sched, bool ALIGN_EPI = false, bool SP2 = false>
; __device__ __forceinline__ void gemm_phase(PG8_LAS unsigned char* lds, const Gemm g, const Sched& S, const Epi& E, int wave_in) {
;     ...
;             const bool last = (t == nt - 2);
;             const char* a1 = cA + (size_t)(t + 1) * kstep;
;             const char* a2 = last ? nA : cA + (size_t)(t + 2) * kstep; const char* b2 = last ? nB : cB + (size_t)(t + 2) * kstep;
;             const char* a3 = a2 + kstep; const char* b3 = b2 + kstep;
;             if (last && has_next) S.a_ready(nxt);
;             if constexpr (SP2) {
;             PG8_LDB(B0, 0, 0); PG8_LDB(B1, 0, 1); PG8_SCHED; PG8_LDA(At, 0, 0); PG8_STAGE(PG8_SA(1, 1), a1 + hstep, voffA);
;             PG8_WAIT_V(8); PG8_WAIT_L(0); PG8_BAR; PG8_MMA(0, 0, At, B0); PG8_MMA(0, 1, At, B1); PG8_BAR; PG8_SCHED;
;             PG8_LDA(At, 0, 1); PG8_STAGE(PG8_SB(0, 0), b2, voffB); PG8_STAGE(PG8_SB(0, 1), b2 + hstep, voffB); PG8_STAGE(PG8_SA(0, 0), a2, voffA);
;             PG8_WAIT_V(8); PG8_WAIT_L(0); PG8_BAR; PG8_MMA(1, 0, At, B0); PG8_MMA(1, 1, At, B1); PG8_BAR; PG8_SCHED;
.LBB0_1009:
	ds_read_b128 v[140:143], v147
	ds_read_b128 v[150:153], v147 offset:1024
	ds_read_b128 v[154:157], v147 offset:2048
	ds_read_b128 v[158:161], v147 offset:3072
	ds_read_b128 v[162:165], v148
	ds_read_b128 v[166:169], v148 offset:1024
	ds_read_b128 v[170:173], v148 offset:2048
	ds_read_b128 v[174:177], v148 offset:3072
	s_add_u32 s18, s16, 0x100
	s_addc_u32 s19, s17, 0
	s_cmpk_eq_i32 s45, 0x54
	s_cselect_b32 s23, s5, s19
	s_cselect_b32 s22, s4, s18
	s_cselect_b32 s21, s15, s44
	s_cselect_b32 s20, s14, s43
	v_lshl_add_u64 v[210:211], s[16:17], 0, v[132:133]
	s_add_i32 m0, s28, 0xc000
	ds_read_b128 v[178:181], v149
	ds_read_b128 v[182:185], v149 offset:1024
	ds_read_b128 v[186:189], v149 offset:2048
	ds_read_b128 v[190:193], v149 offset:3072
	ds_read_b128 v[194:197], v149 offset:4096
	ds_read_b128 v[198:201], v149 offset:5120
	ds_read_b128 v[202:205], v149 offset:6144
	ds_read_b128 v[206:209], v149 offset:7168
	global_load_lds_dwordx4 v[210:211], off
	v_lshl_add_u64 v[210:211], s[16:17], 0, v[134:135]
	s_add_i32 m0, s28, 0xe000
	s_nop 0
	global_load_lds_dwordx4 v[210:211], off
	s_waitcnt vmcnt(8)
	s_waitcnt lgkmcnt(0)
	s_barrier
	s_setprio 1
	s_waitcnt lgkmcnt(0)
	v_mfma_f32_16x16x32_bf16 v[124:127], v[140:143], v[178:181], v[124:127]
	v_mfma_f32_16x16x32_bf16 v[120:123], v[154:157], v[178:181], v[120:123]
	v_mfma_f32_16x16x32_bf16 v[112:115], v[140:143], v[186:189], v[112:115]
	v_mfma_f32_16x16x32_bf16 v[104:107], v[154:157], v[186:189], v[104:107]
	v_mfma_f32_16x16x32_bf16 v[96:99], v[140:143], v[194:197], v[96:99]
	v_mfma_f32_16x16x32_bf16 v[88:91], v[154:157], v[194:197], v[88:91]
	v_mfma_f32_16x16x32_bf16 v[80:83], v[140:143], v[202:205], v[80:83]
	v_mfma_f32_16x16x32_bf16 v[72:75], v[154:157], v[202:205], v[72:75]
	v_mfma_f32_16x16x32_bf16 v[124:127], v[150:153], v[182:185], v[124:127]
	v_mfma_f32_16x16x32_bf16 v[120:123], v[158:161], v[182:185], v[120:123]
	v_mfma_f32_16x16x32_bf16 v[112:115], v[150:153], v[190:193], v[112:115]
	v_mfma_f32_16x16x32_bf16 v[104:107], v[158:161], v[190:193], v[104:107]
	v_mfma_f32_16x16x32_bf16 v[96:99], v[150:153], v[198:201], v[96:99]
	v_mfma_f32_16x16x32_bf16 v[88:91], v[158:161], v[198:201], v[88:91]
	v_mfma_f32_16x16x32_bf16 v[80:83], v[150:153], v[206:209], v[80:83]
	v_mfma_f32_16x16x32_bf16 v[72:75], v[158:161], v[206:209], v[72:75]
	s_setprio 0
	s_setprio 1
	v_mfma_f32_16x16x32_bf16 v[116:119], v[162:165], v[178:181], v[116:119]
	v_mfma_f32_16x16x32_bf16 v[108:111], v[170:173], v[178:181], v[108:111]
	v_mfma_f32_16x16x32_bf16 v[100:103], v[162:165], v[186:189], v[100:103]
	v_mfma_f32_16x16x32_bf16 v[92:95], v[170:173], v[186:189], v[92:95]
	v_mfma_f32_16x16x32_bf16 v[84:87], v[162:165], v[194:197], v[84:87]
	v_mfma_f32_16x16x32_bf16 v[76:79], v[170:173], v[194:197], v[76:79]
	v_mfma_f32_16x16x32_bf16 v[68:71], v[162:165], v[202:205], v[68:71]
	v_mfma_f32_16x16x32_bf16 v[64:67], v[170:173], v[202:205], v[64:67]
	v_mfma_f32_16x16x32_bf16 v[116:119], v[166:169], v[182:185], v[116:119]
	v_mfma_f32_16x16x32_bf16 v[108:111], v[174:177], v[182:185], v[108:111]
	v_mfma_f32_16x16x32_bf16 v[100:103], v[166:169], v[190:193], v[100:103]
	v_mfma_f32_16x16x32_bf16 v[92:95], v[174:177], v[190:193], v[92:95]
	v_mfma_f32_16x16x32_bf16 v[84:87], v[166:169], v[198:201], v[84:87]
	v_mfma_f32_16x16x32_bf16 v[76:79], v[174:177], v[198:201], v[76:79]
	v_mfma_f32_16x16x32_bf16 v[68:71], v[166:169], v[206:209], v[68:71]
	v_mfma_f32_16x16x32_bf16 v[64:67], v[174:177], v[206:209], v[64:67]
	s_setprio 0
	s_barrier
	s_add_i32 s16, s37, s25
	v_lshl_add_u64 v[210:211], s[20:21], 0, v[128:129]
	s_mov_b32 m0, s16
	ds_read_b128 v[178:181], v149 offset:16384
	ds_read_b128 v[182:185], v149 offset:17408
	ds_read_b128 v[186:189], v149 offset:18432
	ds_read_b128 v[190:193], v149 offset:19456
	ds_read_b128 v[194:197], v149 offset:20480
	ds_read_b128 v[198:201], v149 offset:21504
	ds_read_b128 v[202:205], v149 offset:22528
	ds_read_b128 v[206:209], v149 offset:23552
	global_load_lds_dwordx4 v[210:211], off
	s_add_i32 m0, s16, 0x2000
	s_add_u32 s16, s20, 0x160000
	v_lshl_add_u64 v[212:213], s[20:21], 0, v[130:131]
	s_addc_u32 s17, s21, 0
	s_add_i32 s46, s38, s25
	global_load_lds_dwordx4 v[212:213], off
	v_lshl_add_u64 v[214:215], s[16:17], 0, v[128:129]
	s_mov_b32 m0, s46
	v_lshl_add_u64 v[216:217], s[22:23], 0, v[130:131]
	global_load_lds_dwordx4 v[214:215], off
	v_lshl_add_u64 v[214:215], s[16:17], 0, v[130:131]
	s_add_i32 m0, s46, 0x2000
	s_nop 0
	global_load_lds_dwordx4 v[214:215], off
	v_lshl_add_u64 v[214:215], s[22:23], 0, v[128:129]
	s_mov_b32 m0, s28
	s_nop 0
	global_load_lds_dwordx4 v[214:215], off
	s_mov_b32 m0, s29
	s_nop 0
	global_load_lds_dwordx4 v[216:217], off
	s_waitcnt vmcnt(8)
	s_waitcnt lgkmcnt(0)
	s_barrier
; #define PG8_STAGE(bufoff, gbase, voff) do { _Pragma("unroll") for (int _i = 0; _i < 2; ++_i) \
;         __builtin_amdgcn_global_load_lds((const unsigned*)((const char*)(gbase) + (voff)[_i]), (PG8_LAS unsigned*)(lds + (bufoff) + ldsw + _i * 8192), 16, 0, 0); } while (0)
; #define PG8_LDA(dst, b, h) do { _Pragma("unroll") for (int m = 0; m < 4; ++m) _Pragma("unroll") for (int k = 0; k < 2; ++k) dst[m][k] = *(const PG8_LAS bf16x8*)(lds + PG8_SA(b, h) + aoff + m * 2048 + k * 1024); } while (0)
; #define PG8_LDB(dst, b, h) do { _Pragma("unroll") for (int n = 0; n < 2; ++n) _Pragma("unroll") for (int k = 0; k < 2; ++k) dst[n][k] = *(const PG8_LAS bf16x8*)(lds + PG8_SB(b, h) + boff + n * 2048 + k * 1024); } while (0)
; #define PG8_MMA(ai, bj, At, Bt) do { __builtin_amdgcn_s_setprio(1); _Pragma("unroll") for (int m = 0; m < 4; ++m) _Pragma("unroll") for (int n = 0; n < 2; ++n) _Pragma("unroll") for (int k = 0; k < 2; ++k) \
;         acc[ai][bj][m][n] = __builtin_amdgcn_mfma_f32_16x16x32_bf16(Bt[n][k], At[m][k], acc[ai][bj][m][n], 0, 0, 0); __builtin_amdgcn_s_setprio(0); } while (0)
; #define PG8_WAIT_V(n) asm volatile("s_waitcnt vmcnt(" #n ")" ::: "memory")
; #define PG8_WAIT_L(n) asm volatile("s_waitcnt lgkmcnt(" #n ")" ::: "memory")
; #define PG8_BAR __builtin_amdgcn_s_barrier()
; #define PG8_SCHED __builtin_amdgcn_sched_barrier(0)
; template <class Epi, class Sched, bool ALIGN_EPI = false, bool SP2 = false>
; __device__ __forceinline__ void gemm_phase(PG8_LAS unsigned char* lds, const Gemm g, const Sched& S, const Epi& E, int wave_in) {
;     ...
;             PG8_LDA(At, 0, 1); PG8_STAGE(PG8_SB(0, 0), b2, voffB); PG8_STAGE(PG8_SB(0, 1), b2 + hstep, voffB); PG8_STAGE(PG8_SA(0, 0), a2, voffA);
;             PG8_WAIT_V(8); PG8_WAIT_L(0); PG8_BAR; PG8_MMA(1, 0, At, B0); PG8_MMA(1, 1, At, B1); PG8_BAR; PG8_SCHED;
;             PG8_LDB(B0, 1, 0); PG8_LDB(B1, 1, 1); PG8_SCHED; PG8_LDA(At, 1, 0); PG8_STAGE(PG8_SA(0, 1), a2 + hstep, voffA);
;             PG8_WAIT_V(8); PG8_WAIT_L(0); PG8_BAR; PG8_MMA(0, 0, At, B0); PG8_MMA(0, 1, At, B1); PG8_BAR; PG8_SCHED;
	s_setprio 1
	s_waitcnt lgkmcnt(0)
	v_mfma_f32_16x16x32_bf16 v[60:63], v[140:143], v[178:181], v[60:63]
	v_mfma_f32_16x16x32_bf16 v[56:59], v[154:157], v[178:181], v[56:59]
	v_mfma_f32_16x16x32_bf16 v[48:51], v[140:143], v[186:189], v[48:51]
	v_mfma_f32_16x16x32_bf16 v[40:43], v[154:157], v[186:189], v[40:43]
	v_mfma_f32_16x16x32_bf16 v[32:35], v[140:143], v[194:197], v[32:35]
	v_mfma_f32_16x16x32_bf16 v[24:27], v[154:157], v[194:197], v[24:27]
	v_mfma_f32_16x16x32_bf16 v[16:19], v[140:143], v[202:205], v[16:19]
	v_mfma_f32_16x16x32_bf16 v[8:11], v[154:157], v[202:205], v[8:11]
	v_mfma_f32_16x16x32_bf16 v[60:63], v[150:153], v[182:185], v[60:63]
	v_mfma_f32_16x16x32_bf16 v[56:59], v[158:161], v[182:185], v[56:59]
	v_mfma_f32_16x16x32_bf16 v[48:51], v[150:153], v[190:193], v[48:51]
	v_mfma_f32_16x16x32_bf16 v[40:43], v[158:161], v[190:193], v[40:43]
	v_mfma_f32_16x16x32_bf16 v[32:35], v[150:153], v[198:201], v[32:35]
	v_mfma_f32_16x16x32_bf16 v[24:27], v[158:161], v[198:201], v[24:27]
	v_mfma_f32_16x16x32_bf16 v[16:19], v[150:153], v[206:209], v[16:19]
	v_mfma_f32_16x16x32_bf16 v[8:11], v[158:161], v[206:209], v[8:11]
	s_setprio 0
	s_setprio 1
	v_mfma_f32_16x16x32_bf16 v[52:55], v[162:165], v[178:181], v[52:55]
	v_mfma_f32_16x16x32_bf16 v[44:47], v[170:173], v[178:181], v[44:47]
	v_mfma_f32_16x16x32_bf16 v[36:39], v[162:165], v[186:189], v[36:39]
	v_mfma_f32_16x16x32_bf16 v[28:31], v[170:173], v[186:189], v[28:31]
	v_mfma_f32_16x16x32_bf16 v[20:23], v[162:165], v[194:197], v[20:23]
	v_mfma_f32_16x16x32_bf16 v[12:15], v[170:173], v[194:197], v[12:15]
	v_mfma_f32_16x16x32_bf16 v[4:7], v[162:165], v[202:205], v[4:7]
	v_mfma_f32_16x16x32_bf16 v[0:3], v[170:173], v[202:205], v[0:3]
	v_mfma_f32_16x16x32_bf16 v[52:55], v[166:169], v[182:185], v[52:55]
	v_mfma_f32_16x16x32_bf16 v[44:47], v[174:177], v[182:185], v[44:47]
	v_mfma_f32_16x16x32_bf16 v[36:39], v[166:169], v[190:193], v[36:39]
	v_mfma_f32_16x16x32_bf16 v[28:31], v[174:177], v[190:193], v[28:31]
	v_mfma_f32_16x16x32_bf16 v[20:23], v[166:169], v[198:201], v[20:23]
	v_mfma_f32_16x16x32_bf16 v[12:15], v[174:177], v[198:201], v[12:15]
	v_mfma_f32_16x16x32_bf16 v[4:7], v[166:169], v[206:209], v[4:7]
	v_mfma_f32_16x16x32_bf16 v[0:3], v[174:177], v[206:209], v[0:3]
	s_setprio 0
	s_barrier
	s_add_i32 s46, 0, 0x18000
	s_add_i32 s47, 0, 0x1c000
	v_add_u32_e32 v158, s46, v145
	v_add_u32_e32 v174, s47, v145
	ds_read_b128 v[140:143], v158
	ds_read_b128 v[150:153], v158 offset:1024
	ds_read_b128 v[154:157], v158 offset:2048
	ds_read_b128 v[158:161], v158 offset:3072
	ds_read_b128 v[162:165], v174
	ds_read_b128 v[166:169], v174 offset:1024
	ds_read_b128 v[170:173], v174 offset:2048
	ds_read_b128 v[174:177], v174 offset:3072
	s_add_u32 s16, s22, 0x160000
	s_addc_u32 s17, s23, 0
	s_mov_b32 m0, s30
	v_lshl_add_u64 v[218:219], s[16:17], 0, v[128:129]
	ds_read_b128 v[178:181], v149 offset:32768
	ds_read_b128 v[182:185], v149 offset:33792
	ds_read_b128 v[186:189], v149 offset:34816
	ds_read_b128 v[190:193], v149 offset:35840
	ds_read_b128 v[194:197], v149 offset:36864
	ds_read_b128 v[198:201], v149 offset:37888
	ds_read_b128 v[202:205], v149 offset:38912
	ds_read_b128 v[206:209], v149 offset:39936
	global_load_lds_dwordx4 v[218:219], off
	v_lshl_add_u64 v[218:219], s[16:17], 0, v[130:131]
	s_mov_b32 m0, s31
	s_nop 0
	global_load_lds_dwordx4 v[218:219], off
	s_waitcnt vmcnt(8)
	s_waitcnt lgkmcnt(0)
	s_barrier
	s_setprio 1
	s_waitcnt lgkmcnt(0)
	v_mfma_f32_16x16x32_bf16 v[124:127], v[140:143], v[178:181], v[124:127]
	v_mfma_f32_16x16x32_bf16 v[120:123], v[154:157], v[178:181], v[120:123]
	v_mfma_f32_16x16x32_bf16 v[112:115], v[140:143], v[186:189], v[112:115]
	v_mfma_f32_16x16x32_bf16 v[104:107], v[154:157], v[186:189], v[104:107]
	v_mfma_f32_16x16x32_bf16 v[96:99], v[140:143], v[194:197], v[96:99]
	v_mfma_f32_16x16x32_bf16 v[88:91], v[154:157], v[194:197], v[88:91]
	v_mfma_f32_16x16x32_bf16 v[80:83], v[140:143], v[202:205], v[80:83]
	v_mfma_f32_16x16x32_bf16 v[72:75], v[154:157], v[202:205], v[72:75]
	v_mfma_f32_16x16x32_bf16 v[124:127], v[150:153], v[182:185], v[124:127]
	v_mfma_f32_16x16x32_bf16 v[120:123], v[158:161], v[182:185], v[120:123]
	v_mfma_f32_16x16x32_bf16 v[112:115], v[150:153], v[190:193], v[112:115]
	v_mfma_f32_16x16x32_bf16 v[104:107], v[158:161], v[190:193], v[104:107]
	v_mfma_f32_16x16x32_bf16 v[96:99], v[150:153], v[198:201], v[96:99]
	v_mfma_f32_16x16x32_bf16 v[88:91], v[158:161], v[198:201], v[88:91]
	v_mfma_f32_16x16x32_bf16 v[80:83], v[150:153], v[206:209], v[80:83]
	v_mfma_f32_16x16x32_bf16 v[72:75], v[158:161], v[206:209], v[72:75]
	s_setprio 0
	s_setprio 1
	v_mfma_f32_16x16x32_bf16 v[116:119], v[162:165], v[178:181], v[116:119]
	v_mfma_f32_16x16x32_bf16 v[108:111], v[170:173], v[178:181], v[108:111]
	v_mfma_f32_16x16x32_bf16 v[100:103], v[162:165], v[186:189], v[100:103]
	v_mfma_f32_16x16x32_bf16 v[92:95], v[170:173], v[186:189], v[92:95]
	v_mfma_f32_16x16x32_bf16 v[84:87], v[162:165], v[194:197], v[84:87]
	v_mfma_f32_16x16x32_bf16 v[76:79], v[170:173], v[194:197], v[76:79]
	v_mfma_f32_16x16x32_bf16 v[68:71], v[162:165], v[202:205], v[68:71]
	v_mfma_f32_16x16x32_bf16 v[64:67], v[170:173], v[202:205], v[64:67]
	v_mfma_f32_16x16x32_bf16 v[116:119], v[166:169], v[182:185], v[116:119]
	v_mfma_f32_16x16x32_bf16 v[108:111], v[174:177], v[182:185], v[108:111]
	v_mfma_f32_16x16x32_bf16 v[100:103], v[166:169], v[190:193], v[100:103]
	v_mfma_f32_16x16x32_bf16 v[92:95], v[174:177], v[190:193], v[92:95]
	v_mfma_f32_16x16x32_bf16 v[84:87], v[166:169], v[198:201], v[84:87]
	v_mfma_f32_16x16x32_bf16 v[76:79], v[174:177], v[198:201], v[76:79]
	v_mfma_f32_16x16x32_bf16 v[68:71], v[166:169], v[206:209], v[68:71]
	v_mfma_f32_16x16x32_bf16 v[64:67], v[174:177], v[206:209], v[64:67]
	s_setprio 0
	s_barrier
; #define PG8_STAGE(bufoff, gbase, voff) do { _Pragma("unroll") for (int _i = 0; _i < 2; ++_i) \
;         __builtin_amdgcn_global_load_lds((const unsigned*)((const char*)(gbase) + (voff)[_i]), (PG8_LAS unsigned*)(lds + (bufoff) + ldsw + _i * 8192), 16, 0, 0); } while (0)
; #define PG8_LDA(dst, b, h) do { _Pragma("unroll") for (int m = 0; m < 4; ++m) _Pragma("unroll") for (int k = 0; k < 2; ++k) dst[m][k] = *(const PG8_LAS bf16x8*)(lds + PG8_SA(b, h) + aoff + m * 2048 + k * 1024); } while (0)
; #define PG8_MMA(ai, bj, At, Bt) do { __builtin_amdgcn_s_setprio(1); _Pragma("unroll") for (int m = 0; m < 4; ++m) _Pragma("unroll") for (int n = 0; n < 2; ++n) _Pragma("unroll") for (int k = 0; k < 2; ++k) \
;         acc[ai][bj][m][n] = __builtin_amdgcn_mfma_f32_16x16x32_bf16(Bt[n][k], At[m][k], acc[ai][bj][m][n], 0, 0, 0); __builtin_amdgcn_s_setprio(0); } while (0)
; #define PG8_WAIT_V(n) asm volatile("s_waitcnt vmcnt(" #n ")" ::: "memory")
; #define PG8_WAIT_L(n) asm volatile("s_waitcnt lgkmcnt(" #n ")" ::: "memory")
; #define PG8_BAR __builtin_amdgcn_s_barrier()
; #define PG8_SCHED __builtin_amdgcn_sched_barrier(0)
;     __device__ __forceinline__ void operator()(const f32x4 (&acc)[2][2][4][2], const Unit& u, int wr, int wc, int fr, int fq) const {
;     ...
;             for (int m = 0; m < 4; ++m) { const size_t off = (size_t)(u.pm * BM + ai * HALF + wr * 64 + m * 16 + fr) * ldc + col0;
; #pragma unroll
;                 for (int bj = 0; bj < 2; ++bj)
; #pragma unroll
;                     for (int n = 0; n < 2; ++n) { const u32x2 t = *(const u32x2*)(base + off + bj * HALF + n * 16);
; template <class Epi, class Sched, bool ALIGN_EPI = false, bool SP2 = false>
; __device__ __forceinline__ void gemm_phase(PG8_LAS unsigned char* lds, const Gemm g, const Sched& S, const Epi& E, int wave_in) {
;     ...
;             PG8_WAIT_V(8); PG8_WAIT_L(0); PG8_BAR; PG8_MMA(0, 0, At, B0); PG8_MMA(0, 1, At, B1); PG8_BAR; PG8_SCHED;
;             PG8_LDA(At, 1, 1); PG8_STAGE(PG8_SB(1, 0), b3, voffB); PG8_STAGE(PG8_SB(1, 1), b3 + hstep, voffB); PG8_STAGE(PG8_SA(1, 0), a3, voffA);
;             PG8_WAIT_V(8); PG8_WAIT_L(0); PG8_BAR; PG8_MMA(1, 0, At, B0); PG8_MMA(1, 1, At, B1); PG8_BAR; PG8_SCHED;
	s_add_i32 s16, s46, s25
	v_lshl_add_u64 v[210:211], v[210:211], 0, s[6:7]
	s_mov_b32 m0, s16
	ds_read_b128 v[178:181], v149 offset:49152
	ds_read_b128 v[182:185], v149 offset:50176
	ds_read_b128 v[186:189], v149 offset:51200
	ds_read_b128 v[190:193], v149 offset:52224
	ds_read_b128 v[194:197], v149 offset:53248
	ds_read_b128 v[198:201], v149 offset:54272
	ds_read_b128 v[202:205], v149 offset:55296
	ds_read_b128 v[206:209], v149 offset:56320
	global_load_lds_dwordx4 v[210:211], off
	s_add_i32 m0, s16, 0x2000
	s_add_u32 s16, s20, 0x160080
	v_lshl_add_u64 v[210:211], v[212:213], 0, s[6:7]
	s_addc_u32 s17, s21, 0
	s_add_i32 s20, s47, s25
	global_load_lds_dwordx4 v[210:211], off
	v_lshl_add_u64 v[210:211], s[16:17], 0, v[128:129]
	s_mov_b32 m0, s20
	s_nop 0
	global_load_lds_dwordx4 v[210:211], off
	v_lshl_add_u64 v[210:211], s[16:17], 0, v[130:131]
	s_add_i32 m0, s20, 0x2000
	s_nop 0
	global_load_lds_dwordx4 v[210:211], off
	v_lshl_add_u64 v[210:211], v[214:215], 0, s[6:7]
	s_mov_b32 m0, s34
	s_nop 0
	global_load_lds_dwordx4 v[210:211], off
	v_lshl_add_u64 v[210:211], v[216:217], 0, s[6:7]
	s_mov_b32 m0, s35
	s_nop 0
	global_load_lds_dwordx4 v[210:211], off
	s_waitcnt vmcnt(8)
	s_waitcnt lgkmcnt(0)
	s_barrier
	s_setprio 1
	s_waitcnt lgkmcnt(0)
	v_mfma_f32_16x16x32_bf16 v[60:63], v[140:143], v[178:181], v[60:63]
	v_mfma_f32_16x16x32_bf16 v[56:59], v[154:157], v[178:181], v[56:59]
	v_mfma_f32_16x16x32_bf16 v[48:51], v[140:143], v[186:189], v[48:51]
	v_mfma_f32_16x16x32_bf16 v[40:43], v[154:157], v[186:189], v[40:43]
	v_mfma_f32_16x16x32_bf16 v[32:35], v[140:143], v[194:197], v[32:35]
	v_mfma_f32_16x16x32_bf16 v[24:27], v[154:157], v[194:197], v[24:27]
	v_mfma_f32_16x16x32_bf16 v[16:19], v[140:143], v[202:205], v[16:19]
	v_mfma_f32_16x16x32_bf16 v[8:11], v[154:157], v[202:205], v[8:11]
	v_mfma_f32_16x16x32_bf16 v[60:63], v[150:153], v[182:185], v[60:63]
	v_mfma_f32_16x16x32_bf16 v[56:59], v[158:161], v[182:185], v[56:59]
	v_mfma_f32_16x16x32_bf16 v[48:51], v[150:153], v[190:193], v[48:51]
	v_mfma_f32_16x16x32_bf16 v[40:43], v[158:161], v[190:193], v[40:43]
	v_mfma_f32_16x16x32_bf16 v[32:35], v[150:153], v[198:201], v[32:35]
	v_mfma_f32_16x16x32_bf16 v[24:27], v[158:161], v[198:201], v[24:27]
	v_mfma_f32_16x16x32_bf16 v[16:19], v[150:153], v[206:209], v[16:19]
	v_mfma_f32_16x16x32_bf16 v[8:11], v[158:161], v[206:209], v[8:11]
	s_setprio 0
	s_setprio 1
	v_mfma_f32_16x16x32_bf16 v[52:55], v[162:165], v[178:181], v[52:55]
	v_mfma_f32_16x16x32_bf16 v[44:47], v[170:173], v[178:181], v[44:47]
	v_mfma_f32_16x16x32_bf16 v[36:39], v[162:165], v[186:189], v[36:39]
	v_mfma_f32_16x16x32_bf16 v[28:31], v[170:173], v[186:189], v[28:31]
	v_mfma_f32_16x16x32_bf16 v[20:23], v[162:165], v[194:197], v[20:23]
	v_mfma_f32_16x16x32_bf16 v[12:15], v[170:173], v[194:197], v[12:15]
	v_mfma_f32_16x16x32_bf16 v[4:7], v[162:165], v[202:205], v[4:7]
	v_mfma_f32_16x16x32_bf16 v[0:3], v[170:173], v[202:205], v[0:3]
	v_mfma_f32_16x16x32_bf16 v[52:55], v[166:169], v[182:185], v[52:55]
	v_mfma_f32_16x16x32_bf16 v[44:47], v[174:177], v[182:185], v[44:47]
	v_mfma_f32_16x16x32_bf16 v[36:39], v[166:169], v[190:193], v[36:39]
	v_mfma_f32_16x16x32_bf16 v[28:31], v[174:177], v[190:193], v[28:31]
	v_mfma_f32_16x16x32_bf16 v[20:23], v[166:169], v[198:201], v[20:23]
	v_mfma_f32_16x16x32_bf16 v[12:15], v[174:177], v[198:201], v[12:15]
	v_mfma_f32_16x16x32_bf16 v[4:7], v[166:169], v[206:209], v[4:7]
	v_mfma_f32_16x16x32_bf16 v[0:3], v[174:177], v[206:209], v[0:3]
	s_setprio 0
	s_barrier
	s_add_i32 s45, s45, 2
	s_add_u32 s43, s43, 0x100
	s_addc_u32 s44, s44, 0
	s_cmpk_gt_u32 s45, 0x55
	s_mov_b64 s[16:17], s[18:19]
	s_cbranch_scc0 .LBB0_1009
	v_lshl_add_u32 v142, s41, 8, v144
	v_lshl_or_b32 v140, s42, 8, v146
	v_lshlrev_b32_e32 v143, 12, v142
	v_lshl_add_u32 v143, v140, 1, v143
	v_mov_b32_e32 v140, v143
	global_load_dwordx2 v[152:153], v140, s[10:11]
	global_load_dwordx2 v[154:155], v140, s[10:11] offset:32
	global_load_dwordx2 v[156:157], v140, s[10:11] offset:256
	global_load_dwordx2 v[158:159], v140, s[10:11] offset:288
	v_add_u32_e32 v140, 0x10000, v143
	global_load_dwordx2 v[160:161], v140, s[10:11]
	global_load_dwordx2 v[162:163], v140, s[10:11] offset:32
	global_load_dwordx2 v[164:165], v140, s[10:11] offset:256
	global_load_dwordx2 v[166:167], v140, s[10:11] offset:288
	v_add_u32_e32 v140, 0x20000, v143
	global_load_dwordx2 v[168:169], v140, s[10:11]
	global_load_dwordx2 v[170:171], v140, s[10:11] offset:32
	global_load_dwordx2 v[172:173], v140, s[10:11] offset:256
	global_load_dwordx2 v[174:175], v140, s[10:11] offset:288
	v_add_u32_e32 v140, 0x30000, v143
	global_load_dwordx2 v[176:177], v140, s[10:11]
	global_load_dwordx2 v[178:179], v140, s[10:11] offset:32
	global_load_dwordx2 v[180:181], v140, s[10:11] offset:256
	global_load_dwordx2 v[182:183], v140, s[10:11] offset:288
	v_add_u32_e32 v140, 0x80000, v143
	global_load_dwordx2 v[184:185], v140, s[10:11]
	global_load_dwordx2 v[186:187], v140, s[10:11] offset:32
	global_load_dwordx2 v[188:189], v140, s[10:11] offset:256
	global_load_dwordx2 v[190:191], v140, s[10:11] offset:288
	v_add_u32_e32 v140, 0x90000, v143
	global_load_dwordx2 v[192:193], v140, s[10:11]
	global_load_dwordx2 v[194:195], v140, s[10:11] offset:32
	global_load_dwordx2 v[196:197], v140, s[10:11] offset:256
	global_load_dwordx2 v[198:199], v140, s[10:11] offset:288
	v_add_u32_e32 v140, 0xa0000, v143
	global_load_dwordx2 v[200:201], v140, s[10:11]
	global_load_dwordx2 v[202:203], v140, s[10:11] offset:32
	global_load_dwordx2 v[204:205], v140, s[10:11] offset:256
	global_load_dwordx2 v[206:207], v140, s[10:11] offset:288
	v_add_u32_e32 v140, 0xb0000, v143
	global_load_dwordx2 v[208:209], v140, s[10:11]
	global_load_dwordx2 v[210:211], v140, s[10:11] offset:32
	global_load_dwordx2 v[212:213], v140, s[10:11] offset:256
	global_load_dwordx2 v[214:215], v140, s[10:11] offset:288
	s_and_b64 vcc, exec, s[12:13]
	s_cbranch_vccz .LBB0_1012
	s_barrier
